# hot loop heads (4 GEMM K-loops, attention pass-2) aligned to 64 bytes
# baseline (speedup 1.0000x reference)
.LBB0_69:
	s_add_i32 m0, s3, 0x18000
	v_lshl_add_u64 v[0:1], v[0:1], 0, s[66:67]
	s_waitcnt vmcnt(4)
	s_barrier
	global_load_lds_dwordx4 v[0:1], off
	v_lshl_add_u64 v[0:1], v[2:3], 0, s[66:67]
	s_add_i32 m0, s3, 0x1a000
	s_add_i32 s30, s3, 0x8000
	global_load_lds_dwordx4 v[0:1], off
	v_lshl_add_u64 v[0:1], v[4:5], 0, s[66:67]
	s_mov_b32 m0, s30
	s_add_i32 s31, s3, 0xa000
	global_load_lds_dwordx4 v[0:1], off
	v_lshl_add_u64 v[0:1], v[6:7], 0, s[66:67]
	s_mov_b32 m0, s31
	v_and_b32_e32 v19, 15, v15
	global_load_lds_dwordx4 v[0:1], off
	s_add_i32 m0, s3, 0x1c000
	v_lshl_add_u64 v[0:1], v[8:9], 0, s[66:67]
	global_load_lds_dwordx4 v[0:1], off
	v_lshl_add_u64 v[0:1], v[10:11], 0, s[66:67]
	s_add_i32 m0, s3, 0x1e000
	v_and_b32_e32 v20, 48, v15
	global_load_lds_dwordx4 v[0:1], off
	v_lshlrev_b32_e32 v19, 6, v19
	v_lshlrev_b32_e32 v15, 2, v15
	s_lshr_b32 s29, s19, 6
	v_or_b32_e32 v21, v19, v20
	s_lshl_b32 s19, s23, 13
	v_and_b32_e32 v15, 32, v15
	v_bitop3_b32 v19, v19, v15, v20 bitop3:0x36
	v_bitop3_b32 v15, v21, s19, v15 bitop3:0xde
	s_lshl_b32 s19, s22, 12
	s_and_b32 s19, s19, 0x3000
	s_add_i32 s34, s29, -2
	s_add_u32 s16, s18, s16
	s_addc_u32 s17, 0, s17
	s_add_u32 s12, s16, s12
	s_addc_u32 s13, s17, s13
	s_add_u32 s12, s12, s25
	s_addc_u32 s13, s13, 0
	s_add_u32 s12, s80, s12
	s_addc_u32 s13, s81, s13
	v_add_u32_e32 v0, v16, v17
	s_add_u32 s12, s12, 0x80
	v_add_lshl_u32 v0, v0, v18, 1
	v_mov_b32_e32 v1, v133
	s_addc_u32 s13, s13, 0
	v_lshl_add_u64 v[130:131], s[12:13], 0, v[0:1]
	v_add_u32_e32 v0, v12, v13
	s_waitcnt vmcnt(6)
	v_add_lshl_u32 v0, v0, v14, 1
	v_lshl_add_u64 v[150:151], s[12:13], 0, v[0:1]
	v_mov_b32_e32 v0, 0
	v_or_b32_e32 v152, s19, v19
	s_mov_b32 s18, 0
	s_mov_b64 s[12:13], 0
	v_add_u32_e32 v153, 0, v15
	v_mov_b32_e32 v1, v0
	v_mov_b64_e32 v[2:3], 0
	v_mov_b64_e32 v[4:5], 0
	v_mov_b64_e32 v[6:7], 0
	v_mov_b64_e32 v[8:9], 0
	v_mov_b64_e32 v[10:11], 0
	v_mov_b64_e32 v[12:13], 0
	v_mov_b64_e32 v[14:15], 0
	v_mov_b64_e32 v[16:17], 0
	v_mov_b64_e32 v[18:19], 0
	v_mov_b64_e32 v[20:21], 0
	v_mov_b64_e32 v[22:23], 0
	v_mov_b64_e32 v[24:25], 0
	v_mov_b64_e32 v[26:27], 0
	v_mov_b64_e32 v[28:29], 0
	v_mov_b64_e32 v[30:31], 0
	v_mov_b64_e32 v[32:33], 0
	v_mov_b64_e32 v[34:35], 0
	v_mov_b64_e32 v[36:37], 0
	v_mov_b64_e32 v[38:39], 0
	v_mov_b64_e32 v[40:41], 0
	v_mov_b64_e32 v[42:43], 0
	v_mov_b64_e32 v[44:45], 0
	v_mov_b64_e32 v[46:47], 0
	v_mov_b64_e32 v[48:49], 0
	v_mov_b64_e32 v[50:51], 0
	v_mov_b64_e32 v[52:53], 0
	v_mov_b64_e32 v[54:55], 0
	v_mov_b64_e32 v[56:57], 0
	v_mov_b64_e32 v[58:59], 0
	v_mov_b64_e32 v[60:61], 0
	v_mov_b64_e32 v[62:63], 0
	v_mov_b64_e32 v[64:65], 0
	v_mov_b64_e32 v[66:67], 0
	v_mov_b64_e32 v[68:69], 0
	v_mov_b64_e32 v[70:71], 0
	v_mov_b64_e32 v[72:73], 0
	v_mov_b64_e32 v[74:75], 0
	v_mov_b64_e32 v[76:77], 0
	v_mov_b64_e32 v[78:79], 0
	v_mov_b64_e32 v[80:81], 0
	v_mov_b64_e32 v[82:83], 0
	v_mov_b64_e32 v[84:85], 0
	v_mov_b64_e32 v[86:87], 0
	v_mov_b64_e32 v[88:89], 0
	v_mov_b64_e32 v[90:91], 0
	v_mov_b64_e32 v[92:93], 0
	v_mov_b64_e32 v[94:95], 0
	v_mov_b64_e32 v[96:97], 0
	v_mov_b64_e32 v[98:99], 0
	v_mov_b64_e32 v[100:101], 0
	v_mov_b64_e32 v[102:103], 0
	v_mov_b64_e32 v[104:105], 0
	v_mov_b64_e32 v[106:107], 0
	v_mov_b64_e32 v[108:109], 0
	v_mov_b64_e32 v[110:111], 0
	v_mov_b64_e32 v[112:113], 0
	v_mov_b64_e32 v[114:115], 0
	v_mov_b64_e32 v[116:117], 0
	v_mov_b64_e32 v[118:119], 0
	v_mov_b64_e32 v[120:121], 0
	v_mov_b64_e32 v[122:123], 0
	v_mov_b64_e32 v[124:125], 0
	v_mov_b64_e32 v[126:127], 0
	s_barrier
	v_add_u32_e32 v166, 0x10000, v152
	ds_read_b128 v[154:157], v166
	ds_read_b128 v[158:161], v166 offset:1024
	ds_read_b128 v[162:165], v166 offset:2048
	ds_read_b128 v[166:169], v166 offset:3072
	.p2align 6

.LBB0_130:
	s_or_b64 exec, exec, s[4:5]
	v_ashrrev_i32_e32 v42, 2, v40
	v_and_b32_e32 v36, 3, v40
	v_lshrrev_b32_e32 v26, 1, v40
	v_bfe_u32 v27, v40, 1, 3
	v_mad_i64_i32 v[34:35], s[4:5], s34, v42, 0
	v_bitop3_b32 v26, v105, v26, 7 bitop3:0x78
	v_bitop3_b32 v27, v105, v27, 4 bitop3:0x36
	v_lshl_add_u64 v[28:29], v[24:25], 0, v[132:133]
	v_lshl_add_u64 v[34:35], v[34:35], 1, s[16:17]
	v_lshlrev_b32_e32 v132, 5, v36
	v_lshlrev_b32_e32 v121, 4, v26
	v_lshlrev_b32_e32 v119, 4, v27
	global_load_dwordx4 v[24:27], v[28:29], off offset:16
	s_nop 0
	global_load_dwordx4 v[28:31], v[28:29], off
	v_lshl_add_u64 v[38:39], v[34:35], 0, v[132:133]
	v_lshrrev_b32_e32 v17, 3, v40
	v_bfe_u32 v19, v40, 3, 3
	v_lshlrev_b32_e32 v23, 1, v36
	v_lshlrev_b32_e32 v120, 7, v41
	global_load_dwordx4 v[34:37], v[38:39], off offset:16
	s_nop 0
	global_load_dwordx4 v[38:41], v[38:39], off
	v_lshlrev_b32_e32 v22, 7, v42
	v_bitop3_b32 v17, v23, v17, 7 bitop3:0x78
	v_lshl_or_b32 v122, v17, 4, v22
	v_bitop3_b32 v17, v23, v19, 1 bitop3:0x36
	v_lshl_or_b32 v123, v17, 4, v22
	ds_bpermute_b32 v17, v114, v16
	ds_bpermute_b32 v22, v114, v21
	v_max_f32_e32 v16, v16, v16
	v_max_f32_e32 v21, v21, v21
	v_add3_u32 v43, 0, v116, v117
	s_waitcnt lgkmcnt(1)
	v_max_f32_e32 v17, v17, v17
	s_waitcnt lgkmcnt(0)
	v_max_f32_e32 v22, v22, v22
	v_max_f32_e32 v16, v16, v17
	v_max_f32_e32 v21, v21, v22
	ds_bpermute_b32 v17, v115, v16
	ds_bpermute_b32 v22, v115, v21
	s_add_i32 s23, s23, -1
	s_waitcnt vmcnt(2)
	ds_write_b128 v43, v[28:31]
	ds_write_b128 v43, v[24:27] offset:16
	v_add_u32_e32 v24, 0, v122
	s_waitcnt lgkmcnt(3)
	v_max_f32_e32 v17, v17, v17
	s_waitcnt lgkmcnt(2)
	v_max_f32_e32 v22, v22, v22
	v_max_f32_e32 v16, v16, v17
	v_max_f32_e32 v21, v21, v22
	s_waitcnt vmcnt(0)
	ds_write_b128 v24, v[38:41] offset:36864
	v_add_u32_e32 v24, 0, v123
	ds_write_b128 v24, v[34:37] offset:36864
	v_lshlrev_b32_e32 v24, 1, v42
	v_mad_i64_i32 v[24:25], s[4:5], v24, s34, v[132:133]
	v_cndmask_b32_e32 v16, v18, v16, vcc
	v_cndmask_b32_e32 v20, v20, v21, vcc
	v_lshl_add_u64 v[24:25], s[16:17], 0, v[24:25]
	s_mov_b64 s[4:5], 0x90
	v_xor_b32_e32 v16, 0x80000000, v16
	v_xor_b32_e32 v20, 0x80000000, v20
	v_lshl_add_u64 v[106:107], v[24:25], 0, s[4:5]
	s_mov_b64 s[4:5], 0x4010
	v_mov_b32_e32 v24, 0
	v_mov_b32_e32 v17, v16
	v_mov_b32_e32 v18, v16
	v_mov_b32_e32 v19, v16
	v_mov_b32_e32 v21, v20
	v_mov_b32_e32 v22, v20
	v_mov_b32_e32 v23, v20
	v_lshl_add_u64 v[108:109], v[32:33], 0, s[4:5]
	s_mov_b32 s4, 0
	v_mov_b32_e32 v25, v24
	v_mov_b32_e32 v26, v24
	v_mov_b32_e32 v27, v24
	v_mov_b32_e32 v28, v24
	v_mov_b32_e32 v29, v24
	v_mov_b32_e32 v30, v24
	v_mov_b32_e32 v31, v24
	v_mov_b32_e32 v32, v24
	v_mov_b32_e32 v33, v24
	v_mov_b32_e32 v34, v24
	v_mov_b32_e32 v35, v24
	v_mov_b32_e32 v36, v24
	v_mov_b32_e32 v37, v24
	v_mov_b32_e32 v38, v24
	v_mov_b32_e32 v39, v24
	v_mov_b32_e32 v56, v24
	v_mov_b32_e32 v57, v24
	v_mov_b32_e32 v58, v24
	v_mov_b32_e32 v59, v24
	v_mov_b32_e32 v60, v24
	v_mov_b32_e32 v61, v24
	v_mov_b32_e32 v62, v24
	v_mov_b32_e32 v63, v24
	v_mov_b32_e32 v68, v24
	v_mov_b32_e32 v69, v24
	v_mov_b32_e32 v70, v24
	v_mov_b32_e32 v71, v24
	v_mov_b32_e32 v72, v24
	v_mov_b32_e32 v73, v24
	v_mov_b32_e32 v74, v24
	v_mov_b32_e32 v75, v24
	v_mov_b32_e32 v40, v24
	v_mov_b32_e32 v41, v24
	v_mov_b32_e32 v42, v24
	v_mov_b32_e32 v43, v24
	v_mov_b32_e32 v44, v24
	v_mov_b32_e32 v45, v24
	v_mov_b32_e32 v46, v24
	v_mov_b32_e32 v47, v24
	v_mov_b32_e32 v48, v24
	v_mov_b32_e32 v49, v24
	v_mov_b32_e32 v50, v24
	v_mov_b32_e32 v51, v24
	v_mov_b32_e32 v52, v24
	v_mov_b32_e32 v53, v24
	v_mov_b32_e32 v54, v24
	v_mov_b32_e32 v55, v24
	v_mov_b32_e32 v64, v24
	v_mov_b32_e32 v65, v24
	v_mov_b32_e32 v66, v24
	v_mov_b32_e32 v67, v24
	v_mov_b32_e32 v76, v24
	v_mov_b32_e32 v77, v24
	v_mov_b32_e32 v78, v24
	v_mov_b32_e32 v79, v24
	v_mov_b32_e32 v80, v24
	v_mov_b32_e32 v81, v24
	v_mov_b32_e32 v82, v24
	v_mov_b32_e32 v83, v24
	v_mov_b32_e32 v84, v24
	v_mov_b32_e32 v85, v24
	v_mov_b32_e32 v86, v24
	v_mov_b32_e32 v87, v24
	v_mov_b32_e32 v110, v24
	v_mov_b32_e32 v111, v24
	s_waitcnt lgkmcnt(0)
	s_barrier
	.p2align 6

.LBB0_144:
	s_ashr_i32 s19, s18, 31
	v_cmp_lt_i64_e32 vcc, s[10:11], v[140:141]
	s_lshl_b64 s[10:11], s[18:19], 19
	s_add_u32 s22, s86, s10
	s_addc_u32 s23, s87, s11
	s_and_b64 s[10:11], vcc, exec
	s_cselect_b32 s9, s23, s3
	s_cselect_b32 s12, s22, s2
	s_cmp_eq_u32 s16, 5
	s_cselect_b32 s17, 7, s16
	s_cmp_eq_u32 s16, 7
	s_cselect_b32 s16, 5, s17
	s_ashr_i32 s17, s16, 31
	s_lshl_b64 s[10:11], s[16:17], 19
	s_add_u32 s24, s41, s10
	s_addc_u32 s25, s14, s11
	s_and_b64 s[10:11], vcc, exec
	s_cselect_b32 s13, s25, s7
	s_cselect_b32 s17, s24, s6
	s_add_u32 s2, s2, 0x40080
	s_addc_u32 s3, s3, 0
	s_add_u32 s19, s6, 0x100
	v_mov_b32_e32 v0, 0
	s_addc_u32 s27, s7, 0
	s_waitcnt lgkmcnt(0)
	s_mov_b32 s28, -2
	v_mov_b32_e32 v1, v0
	v_mov_b64_e32 v[2:3], 0
	v_mov_b64_e32 v[4:5], 0
	v_mov_b64_e32 v[6:7], 0
	v_mov_b64_e32 v[8:9], 0
	v_mov_b64_e32 v[10:11], 0
	v_mov_b64_e32 v[12:13], 0
	v_mov_b64_e32 v[14:15], 0
	v_mov_b64_e32 v[16:17], 0
	v_mov_b64_e32 v[18:19], 0
	v_mov_b64_e32 v[20:21], 0
	v_mov_b64_e32 v[22:23], 0
	v_mov_b64_e32 v[24:25], 0
	v_mov_b64_e32 v[26:27], 0
	v_mov_b64_e32 v[28:29], 0
	v_mov_b64_e32 v[30:31], 0
	v_mov_b64_e32 v[32:33], 0
	v_mov_b64_e32 v[34:35], 0
	v_mov_b64_e32 v[36:37], 0
	v_mov_b64_e32 v[38:39], 0
	v_mov_b64_e32 v[40:41], 0
	v_mov_b64_e32 v[42:43], 0
	v_mov_b64_e32 v[44:45], 0
	v_mov_b64_e32 v[46:47], 0
	v_mov_b64_e32 v[48:49], 0
	v_mov_b64_e32 v[50:51], 0
	v_mov_b64_e32 v[52:53], 0
	v_mov_b64_e32 v[54:55], 0
	v_mov_b64_e32 v[56:57], 0
	v_mov_b64_e32 v[58:59], 0
	v_mov_b64_e32 v[60:61], 0
	v_mov_b64_e32 v[62:63], 0
	v_mov_b64_e32 v[64:65], 0
	v_mov_b64_e32 v[66:67], 0
	v_mov_b64_e32 v[68:69], 0
	v_mov_b64_e32 v[70:71], 0
	v_mov_b64_e32 v[72:73], 0
	v_mov_b64_e32 v[74:75], 0
	v_mov_b64_e32 v[76:77], 0
	v_mov_b64_e32 v[78:79], 0
	v_mov_b64_e32 v[80:81], 0
	v_mov_b64_e32 v[82:83], 0
	v_mov_b64_e32 v[84:85], 0
	v_mov_b64_e32 v[86:87], 0
	v_mov_b64_e32 v[88:89], 0
	v_mov_b64_e32 v[90:91], 0
	v_mov_b64_e32 v[92:93], 0
	v_mov_b64_e32 v[94:95], 0
	v_mov_b64_e32 v[96:97], 0
	v_mov_b64_e32 v[98:99], 0
	v_mov_b64_e32 v[100:101], 0
	v_mov_b64_e32 v[102:103], 0
	v_mov_b64_e32 v[104:105], 0
	v_mov_b64_e32 v[106:107], 0
	v_mov_b64_e32 v[108:109], 0
	v_mov_b64_e32 v[110:111], 0
	v_mov_b64_e32 v[112:113], 0
	v_mov_b64_e32 v[114:115], 0
	v_mov_b64_e32 v[116:117], 0
	v_mov_b64_e32 v[118:119], 0
	v_mov_b64_e32 v[120:121], 0
	v_mov_b64_e32 v[122:123], 0
	v_mov_b64_e32 v[124:125], 0
	v_mov_b64_e32 v[126:127], 0
	v_add_u32_e32 v166, 0x10000, v215
	ds_read_b128 v[128:131], v166
	ds_read_b128 v[158:161], v166 offset:1024
	ds_read_b128 v[162:165], v166 offset:2048
	ds_read_b128 v[166:169], v166 offset:3072
	.p2align 6

.LBB0_1103:
	s_ashr_i32 s9, s8, 31
	v_cmp_lt_i64_e32 vcc, s[10:11], v[144:145]
	s_lshl_b64 s[10:11], s[8:9], 19
	s_add_u32 s10, s15, s10
	s_addc_u32 s11, s26, s11
	s_and_b64 s[12:13], vcc, exec
	s_cselect_b32 s9, s11, s19
	s_cselect_b32 s42, s10, s18
	s_ashr_i32 s7, s6, 31
	s_lshl_b64 s[12:13], s[6:7], 19
	s_add_u32 s12, s27, s12
	s_addc_u32 s13, s28, s13
	s_and_b64 s[24:25], vcc, exec
	s_cselect_b32 s7, s13, s23
	s_cselect_b32 s43, s12, s22
	s_add_u32 s18, s18, 0x40080
	s_addc_u32 s19, s19, 0
	s_add_u32 s44, s22, 0x100
	v_mov_b32_e32 v0, 0
	s_addc_u32 s45, s23, 0
	s_mov_b32 s46, -2
	v_mov_b32_e32 v1, v0
	v_mov_b64_e32 v[2:3], 0
	v_mov_b64_e32 v[4:5], 0
	v_mov_b64_e32 v[6:7], 0
	v_mov_b64_e32 v[8:9], 0
	v_mov_b64_e32 v[10:11], 0
	v_mov_b64_e32 v[12:13], 0
	v_mov_b64_e32 v[14:15], 0
	v_mov_b64_e32 v[16:17], 0
	v_mov_b64_e32 v[18:19], 0
	v_mov_b64_e32 v[20:21], 0
	v_mov_b64_e32 v[22:23], 0
	v_mov_b64_e32 v[24:25], 0
	v_mov_b64_e32 v[26:27], 0
	v_mov_b64_e32 v[28:29], 0
	v_mov_b64_e32 v[30:31], 0
	v_mov_b64_e32 v[32:33], 0
	v_mov_b64_e32 v[34:35], 0
	v_mov_b64_e32 v[36:37], 0
	v_mov_b64_e32 v[38:39], 0
	v_mov_b64_e32 v[40:41], 0
	v_mov_b64_e32 v[42:43], 0
	v_mov_b64_e32 v[44:45], 0
	v_mov_b64_e32 v[46:47], 0
	v_mov_b64_e32 v[48:49], 0
	v_mov_b64_e32 v[50:51], 0
	v_mov_b64_e32 v[52:53], 0
	v_mov_b64_e32 v[54:55], 0
	v_mov_b64_e32 v[56:57], 0
	v_mov_b64_e32 v[58:59], 0
	v_mov_b64_e32 v[60:61], 0
	v_mov_b64_e32 v[62:63], 0
	v_mov_b64_e32 v[64:65], 0
	v_mov_b64_e32 v[66:67], 0
	v_mov_b64_e32 v[68:69], 0
	v_mov_b64_e32 v[70:71], 0
	v_mov_b64_e32 v[72:73], 0
	v_mov_b64_e32 v[74:75], 0
	v_mov_b64_e32 v[76:77], 0
	v_mov_b64_e32 v[78:79], 0
	v_mov_b64_e32 v[80:81], 0
	v_mov_b64_e32 v[82:83], 0
	v_mov_b64_e32 v[84:85], 0
	v_mov_b64_e32 v[86:87], 0
	v_mov_b64_e32 v[88:89], 0
	v_mov_b64_e32 v[90:91], 0
	v_mov_b64_e32 v[92:93], 0
	v_mov_b64_e32 v[94:95], 0
	v_mov_b64_e32 v[96:97], 0
	v_mov_b64_e32 v[98:99], 0
	v_mov_b64_e32 v[100:101], 0
	v_mov_b64_e32 v[102:103], 0
	v_mov_b64_e32 v[104:105], 0
	v_mov_b64_e32 v[106:107], 0
	v_mov_b64_e32 v[108:109], 0
	v_mov_b64_e32 v[110:111], 0
	v_mov_b64_e32 v[112:113], 0
	v_mov_b64_e32 v[114:115], 0
	v_mov_b64_e32 v[116:117], 0
	v_mov_b64_e32 v[118:119], 0
	v_mov_b64_e32 v[120:121], 0
	v_mov_b64_e32 v[122:123], 0
	v_mov_b64_e32 v[124:125], 0
	v_mov_b64_e32 v[126:127], 0
	v_add_u32_e32 v168, 0x10000, v154
	ds_read_b128 v[156:159], v168
	ds_read_b128 v[160:163], v168 offset:1024
	ds_read_b128 v[164:167], v168 offset:2048
	ds_read_b128 v[168:171], v168 offset:3072
	.p2align 6

.LBB0_1233:
	s_add_u32 s8, s12, 0x80
	s_addc_u32 s9, s13, 0
	s_add_u32 s38, s10, 0x100
	v_mov_b32_e32 v0, 0
	s_addc_u32 s39, s11, 0
	s_mov_b32 s10, 0
	v_mov_b32_e32 v1, v0
	v_mov_b64_e32 v[2:3], 0
	v_mov_b64_e32 v[4:5], 0
	v_mov_b64_e32 v[6:7], 0
	v_mov_b64_e32 v[8:9], 0
	v_mov_b64_e32 v[10:11], 0
	v_mov_b64_e32 v[12:13], 0
	v_mov_b64_e32 v[14:15], 0
	v_mov_b64_e32 v[16:17], 0
	v_mov_b64_e32 v[18:19], 0
	v_mov_b64_e32 v[20:21], 0
	v_mov_b64_e32 v[22:23], 0
	v_mov_b64_e32 v[24:25], 0
	v_mov_b64_e32 v[26:27], 0
	v_mov_b64_e32 v[28:29], 0
	v_mov_b64_e32 v[30:31], 0
	v_mov_b64_e32 v[32:33], 0
	v_mov_b64_e32 v[34:35], 0
	v_mov_b64_e32 v[36:37], 0
	v_mov_b64_e32 v[38:39], 0
	v_mov_b64_e32 v[40:41], 0
	v_mov_b64_e32 v[42:43], 0
	v_mov_b64_e32 v[44:45], 0
	v_mov_b64_e32 v[46:47], 0
	v_mov_b64_e32 v[48:49], 0
	v_mov_b64_e32 v[50:51], 0
	v_mov_b64_e32 v[52:53], 0
	v_mov_b64_e32 v[54:55], 0
	v_mov_b64_e32 v[56:57], 0
	v_mov_b64_e32 v[58:59], 0
	v_mov_b64_e32 v[60:61], 0
	v_mov_b64_e32 v[62:63], 0
	v_mov_b64_e32 v[64:65], 0
	v_mov_b64_e32 v[66:67], 0
	v_mov_b64_e32 v[68:69], 0
	v_mov_b64_e32 v[70:71], 0
	v_mov_b64_e32 v[72:73], 0
	v_mov_b64_e32 v[74:75], 0
	v_mov_b64_e32 v[76:77], 0
	v_mov_b64_e32 v[78:79], 0
	v_mov_b64_e32 v[80:81], 0
	v_mov_b64_e32 v[82:83], 0
	v_mov_b64_e32 v[84:85], 0
	v_mov_b64_e32 v[86:87], 0
	v_mov_b64_e32 v[88:89], 0
	v_mov_b64_e32 v[90:91], 0
	v_mov_b64_e32 v[92:93], 0
	v_mov_b64_e32 v[94:95], 0
	v_mov_b64_e32 v[96:97], 0
	v_mov_b64_e32 v[98:99], 0
	v_mov_b64_e32 v[100:101], 0
	v_mov_b64_e32 v[102:103], 0
	v_mov_b64_e32 v[104:105], 0
	v_mov_b64_e32 v[106:107], 0
	v_mov_b64_e32 v[108:109], 0
	v_mov_b64_e32 v[110:111], 0
	v_mov_b64_e32 v[112:113], 0
	v_mov_b64_e32 v[114:115], 0
	v_mov_b64_e32 v[116:117], 0
	v_mov_b64_e32 v[118:119], 0
	v_mov_b64_e32 v[120:121], 0
	v_mov_b64_e32 v[122:123], 0
	v_mov_b64_e32 v[124:125], 0
	v_mov_b64_e32 v[126:127], 0
	v_add_u32_e32 v168, 0x10000, v154
	ds_read_b128 v[156:159], v168
	ds_read_b128 v[160:163], v168 offset:1024
	ds_read_b128 v[164:167], v168 offset:2048
	ds_read_b128 v[168:171], v168 offset:3072
	.p2align 6
